# IN epilogue rotary path: frequency vector loaded once per unit instead of per piece, per-piece vmcnt(0) dropped (on top of shorter barrier chain)
# speedup vs baseline: 1.0074x; 1.0023x over previous
.LBB0_178:
	global_load_dwordx4 v[186:189], v[140:141], off offset:256
	v_lshl_add_u32 v150, s8, 8, v160
	v_and_b32_e32 v136, 0x7cf, v150
	v_cvt_f32_u32_e32 v136, v136
	s_lshl_b32 s17, s6, 8
	s_add_i32 s2, s17, 0xfffff800
	v_ashrrev_i32_e32 v151, 31, v150
	s_lshr_b32 s28, s2, 10
	v_lshlrev_b64 v[156:157], 11, v[150:151]
	v_cmp_gt_i32_e32 vcc, s37, v150
	v_lshlrev_b64 v[154:155], 10, v[150:151]
	v_or_b32_e32 v151, s17, v162
	s_mul_hi_u32 s19, s28, 0x2040000
	s_mul_i32 s28, s28, 0x2040000
	v_cndmask_b32_e32 v168, v166, v136, vcc
	v_cmp_lt_i32_e64 s[8:9], s47, v151
	s_and_saveexec_b64 s[6:7], s[8:9]
	s_xor_b64 s[6:7], exec, s[6:7]
	s_cbranch_execz .LBB0_183
	s_cmpk_gt_u32 s17, 0x7ff
	s_mov_b64 s[24:25], -1
	s_cbranch_scc0 .LBB0_181
	s_add_u32 s24, s40, s28
	v_and_b32_e32 v136, 0x378, v151
	s_addc_u32 s25, s41, s19
	v_lshl_add_u64 v[152:153], s[24:25], 0, v[156:157]
	v_lshlrev_b32_e32 v136, 1, v136
	v_lshl_add_u64 v[152:153], v[152:153], 0, v[136:137]
	v_cvt_pk_bf16_f32 v170, v124, v125
	v_cvt_pk_bf16_f32 v171, v126, v127
	v_cvt_pk_bf16_f32 v172, v120, v121
	v_cvt_pk_bf16_f32 v173, v122, v123
	global_store_dwordx4 v[152:153], v[170:173], off
	s_mov_b64 s[24:25], 0
.LBB0_181:
	s_andn2_b64 vcc, exec, s[24:25]
	s_cbranch_vccnz .LBB0_183
	s_cmpk_gt_u32 s17, 0x5ff
	s_cselect_b64 vcc, -1, 0
	s_and_b64 s[24:25], vcc, exec
	s_cselect_b32 s24, 0x2040000, s49
	s_cselect_b32 s2, s48, 0xfffffc00
	s_add_u32 s24, s14, s24
	v_add_u32_e32 v136, s2, v151
	s_addc_u32 s25, s15, 0
	v_and_b32_e32 v136, 0xffffff00, v136
	v_lshl_add_u64 v[158:159], s[24:25], 0, v[154:155]
	v_lshl_add_u64 v[158:159], v[136:137], 1, v[158:159]
	v_lshlrev_b32_e32 v136, 1, v138
	v_lshl_add_u64 v[158:159], v[158:159], 0, v[136:137]
	v_cndmask_b32_e32 v152, 1.0, v167, vcc
	s_waitcnt vmcnt(0)
	v_mul_f32_e32 v136, v168, v186
	v_mul_f32_e32 v153, v168, v187
	v_mul_f32_e32 v169, v168, v188
	v_mul_f32_e32 v170, v168, v189
	v_mul_f32_e32 v171, 0.15915494, v136
	v_mul_f32_e32 v172, 0.15915494, v153
	v_mul_f32_e32 v173, 0.15915494, v169
	v_mul_f32_e32 v174, 0.15915494, v170
	v_rndne_f32_e32 v171, v171
	v_rndne_f32_e32 v172, v172
	v_rndne_f32_e32 v173, v173
	v_rndne_f32_e32 v174, v174
	v_fmac_f32_e32 v136, 0xc0c90fdb, v171
	v_fmac_f32_e32 v153, 0xc0c90fdb, v172
	v_fmac_f32_e32 v169, 0xc0c90fdb, v173
	v_fmac_f32_e32 v170, 0xc0c90fdb, v174
	v_fmac_f32_e32 v136, 0x343bbd2e, v171
	v_fmac_f32_e32 v153, 0x343bbd2e, v172
	v_fmac_f32_e32 v169, 0x343bbd2e, v173
	v_fmac_f32_e32 v170, 0x343bbd2e, v174
	v_mul_f32_e32 v136, 0.15915494, v136
	v_mul_f32_e32 v153, 0.15915494, v153
	v_mul_f32_e32 v169, 0.15915494, v169
	v_mul_f32_e32 v177, 0.15915494, v170
	v_sin_f32_e32 v170, v136
	v_cos_f32_e32 v171, v136
	v_sin_f32_e32 v172, v153
	v_cos_f32_e32 v173, v153
	v_sin_f32_e32 v174, v169
	v_cos_f32_e32 v175, v169
	v_sin_f32_e32 v178, v177
	v_cos_f32_e32 v179, v177
	v_pk_mul_f32 v[170:171], v[152:153], v[170:171] op_sel_hi:[0,1]
	v_pk_mul_f32 v[172:173], v[152:153], v[172:173] op_sel_hi:[0,1]
	v_pk_mul_f32 v[174:175], v[152:153], v[174:175] op_sel_hi:[0,1]
	v_pk_mul_f32 v[152:153], v[152:153], v[178:179] op_sel_hi:[0,1]
	v_pk_mul_f32 v[178:179], v[124:125], v[170:171] op_sel:[0,1] op_sel_hi:[1,0]
	v_pk_mul_f32 v[170:171], v[124:125], v[170:171]
	v_pk_mul_f32 v[180:181], v[126:127], v[172:173] op_sel:[0,1] op_sel_hi:[1,0]
	v_pk_mul_f32 v[172:173], v[126:127], v[172:173]
	v_pk_mul_f32 v[182:183], v[120:121], v[174:175] op_sel:[0,1] op_sel_hi:[1,0]
	v_pk_mul_f32 v[174:175], v[120:121], v[174:175]
	v_pk_mul_f32 v[184:185], v[122:123], v[152:153] op_sel:[0,1] op_sel_hi:[1,0]
	v_pk_mul_f32 v[152:153], v[122:123], v[152:153]
	v_sub_f32_e32 v136, v178, v179
	v_add_f32_e32 v169, v171, v170
	v_sub_f32_e32 v170, v180, v181
	v_add_f32_e32 v171, v173, v172
	v_sub_f32_e32 v172, v182, v183
	v_add_f32_e32 v173, v175, v174
	v_sub_f32_e32 v174, v184, v185
	v_add_f32_e32 v175, v153, v152
	v_cvt_pk_bf16_f32 v152, v136, v170
	v_cvt_pk_bf16_f32 v153, v172, v174
	v_cvt_pk_bf16_f32 v170, v169, v171
	v_cvt_pk_bf16_f32 v171, v173, v175
	global_store_dwordx2 v[158:159], v[152:153], off
	global_store_dwordx2 v[158:159], v[170:171], off offset:128

.LBB0_188:
	s_andn2_b64 vcc, exec, s[26:27]
	s_cbranch_vccnz .LBB0_190
	s_cmpk_gt_u32 s17, 0x5ff
	s_cselect_b64 vcc, -1, 0
	s_and_b64 s[26:27], vcc, exec
	s_cselect_b32 s26, 0x2040000, s49
	s_cselect_b32 s2, s48, 0xfffffc00
	s_add_u32 s26, s14, s26
	v_add_u32_e32 v121, s2, v122
	s_addc_u32 s27, s15, 0
	v_and_b32_e32 v136, 0xffffff80, v121
	v_lshl_add_u64 v[154:155], s[26:27], 0, v[154:155]
	v_lshl_add_u64 v[154:155], v[136:137], 1, v[154:155]
	v_lshlrev_b32_e32 v136, 1, v138
	v_lshl_add_u64 v[154:155], v[154:155], 0, v[136:137]
	v_cndmask_b32_e32 v120, 1.0, v167, vcc
	v_mul_f32_e32 v121, v168, v186
	v_mul_f32_e32 v123, v168, v187
	v_mul_f32_e32 v124, v168, v188
	v_mul_f32_e32 v125, v168, v189
	v_mul_f32_e32 v126, 0.15915494, v121
	v_mul_f32_e32 v127, 0.15915494, v123
	v_mul_f32_e32 v136, 0.15915494, v124
	v_mul_f32_e32 v156, 0.15915494, v125
	v_rndne_f32_e32 v126, v126
	v_rndne_f32_e32 v127, v127
	v_rndne_f32_e32 v136, v136
	v_rndne_f32_e32 v156, v156
	v_fmac_f32_e32 v121, 0xc0c90fdb, v126
	v_fmac_f32_e32 v123, 0xc0c90fdb, v127
	v_fmac_f32_e32 v124, 0xc0c90fdb, v136
	v_fmac_f32_e32 v125, 0xc0c90fdb, v156
	v_fmac_f32_e32 v121, 0x343bbd2e, v126
	v_fmac_f32_e32 v123, 0x343bbd2e, v127
	v_fmac_f32_e32 v124, 0x343bbd2e, v136
	v_fmac_f32_e32 v125, 0x343bbd2e, v156
	v_mul_f32_e32 v121, 0.15915494, v121
	v_mul_f32_e32 v123, 0.15915494, v123
	v_mul_f32_e32 v136, 0.15915494, v124
	v_mul_f32_e32 v159, 0.15915494, v125
	v_sin_f32_e32 v124, v121
	v_cos_f32_e32 v125, v121
	v_sin_f32_e32 v126, v123
	v_cos_f32_e32 v127, v123
	v_sin_f32_e32 v156, v136
	v_cos_f32_e32 v157, v136
	v_sin_f32_e32 v158, v159
	v_cos_f32_e32 v159, v159
	v_pk_mul_f32 v[124:125], v[120:121], v[124:125] op_sel_hi:[0,1]
	v_pk_mul_f32 v[126:127], v[120:121], v[126:127] op_sel_hi:[0,1]
	v_pk_mul_f32 v[156:157], v[120:121], v[156:157] op_sel_hi:[0,1]
	v_pk_mul_f32 v[120:121], v[120:121], v[158:159] op_sel_hi:[0,1]
	v_pk_mul_f32 v[158:159], v[116:117], v[124:125] op_sel:[0,1] op_sel_hi:[1,0]
	v_pk_mul_f32 v[124:125], v[116:117], v[124:125]
	v_pk_mul_f32 v[168:169], v[118:119], v[126:127] op_sel:[0,1] op_sel_hi:[1,0]
	v_pk_mul_f32 v[126:127], v[118:119], v[126:127]
	v_pk_mul_f32 v[170:171], v[112:113], v[156:157] op_sel:[0,1] op_sel_hi:[1,0]
	v_pk_mul_f32 v[156:157], v[112:113], v[156:157]
	v_pk_mul_f32 v[172:173], v[114:115], v[120:121] op_sel:[0,1] op_sel_hi:[1,0]
	v_pk_mul_f32 v[120:121], v[114:115], v[120:121]
	v_sub_f32_e32 v123, v158, v159
	v_add_f32_e32 v124, v125, v124
	v_sub_f32_e32 v125, v168, v169
	v_add_f32_e32 v126, v127, v126
	v_sub_f32_e32 v127, v170, v171
	v_add_f32_e32 v136, v157, v156
	v_sub_f32_e32 v156, v172, v173
	v_add_f32_e32 v157, v121, v120
	v_cvt_pk_bf16_f32 v120, v123, v125
	v_cvt_pk_bf16_f32 v121, v127, v156
	v_cvt_pk_bf16_f32 v124, v124, v126
	v_cvt_pk_bf16_f32 v125, v136, v157
	global_store_dwordx2 v[154:155], v[120:121], off
	global_store_dwordx2 v[154:155], v[124:125], off offset:128

.LBB0_195:
	s_andn2_b64 vcc, exec, s[26:27]
	s_cbranch_vccnz .LBB0_197
	s_cmpk_gt_u32 s17, 0x5ff
	s_cselect_b64 vcc, -1, 0
	s_and_b64 s[26:27], vcc, exec
	s_cselect_b32 s26, 0x2040000, s49
	s_cselect_b32 s2, s48, 0xfffffc00
	s_add_u32 s26, s14, s26
	v_add_u32_e32 v117, s2, v151
	s_addc_u32 s27, s15, 0
	v_and_b32_e32 v136, 0xffffff00, v117
	v_lshl_add_u64 v[154:155], s[26:27], 0, v[112:113]
	v_lshl_add_u64 v[154:155], v[136:137], 1, v[154:155]
	v_lshlrev_b32_e32 v136, 1, v138
	v_lshl_add_u64 v[154:155], v[154:155], 0, v[136:137]
	v_cndmask_b32_e32 v116, 1.0, v167, vcc
	v_mul_f32_e32 v117, v118, v186
	v_mul_f32_e32 v119, v118, v187
	v_mul_f32_e32 v123, v118, v188
	v_mul_f32_e32 v124, v118, v189
	v_mul_f32_e32 v125, 0.15915494, v117
	v_mul_f32_e32 v126, 0.15915494, v119
	v_mul_f32_e32 v127, 0.15915494, v123
	v_mul_f32_e32 v136, 0.15915494, v124
	v_rndne_f32_e32 v125, v125
	v_rndne_f32_e32 v126, v126
	v_rndne_f32_e32 v127, v127
	v_rndne_f32_e32 v136, v136
	v_fmac_f32_e32 v117, 0xc0c90fdb, v125
	v_fmac_f32_e32 v119, 0xc0c90fdb, v126
	v_fmac_f32_e32 v123, 0xc0c90fdb, v127
	v_fmac_f32_e32 v124, 0xc0c90fdb, v136
	v_fmac_f32_e32 v117, 0x343bbd2e, v125
	v_fmac_f32_e32 v119, 0x343bbd2e, v126
	v_fmac_f32_e32 v123, 0x343bbd2e, v127
	v_fmac_f32_e32 v124, 0x343bbd2e, v136
	v_mul_f32_e32 v117, 0.15915494, v117
	v_mul_f32_e32 v119, 0.15915494, v119
	v_mul_f32_e32 v123, 0.15915494, v123
	v_mul_f32_e32 v136, 0.15915494, v124
	v_sin_f32_e32 v124, v117
	v_cos_f32_e32 v125, v117
	v_sin_f32_e32 v126, v119
	v_cos_f32_e32 v127, v119
	v_sin_f32_e32 v156, v123
	v_cos_f32_e32 v157, v123
	v_sin_f32_e32 v158, v136
	v_cos_f32_e32 v159, v136
	v_pk_mul_f32 v[124:125], v[116:117], v[124:125] op_sel_hi:[0,1]
	v_pk_mul_f32 v[126:127], v[116:117], v[126:127] op_sel_hi:[0,1]
	v_pk_mul_f32 v[156:157], v[116:117], v[156:157] op_sel_hi:[0,1]
	v_pk_mul_f32 v[116:117], v[116:117], v[158:159] op_sel_hi:[0,1]
	v_pk_mul_f32 v[158:159], v[108:109], v[124:125] op_sel:[0,1] op_sel_hi:[1,0]
	v_pk_mul_f32 v[124:125], v[108:109], v[124:125]
	v_pk_mul_f32 v[168:169], v[110:111], v[126:127] op_sel:[0,1] op_sel_hi:[1,0]
	v_pk_mul_f32 v[126:127], v[110:111], v[126:127]
	v_pk_mul_f32 v[170:171], v[104:105], v[156:157] op_sel:[0,1] op_sel_hi:[1,0]
	v_pk_mul_f32 v[156:157], v[104:105], v[156:157]
	v_pk_mul_f32 v[172:173], v[106:107], v[116:117] op_sel:[0,1] op_sel_hi:[1,0]
	v_pk_mul_f32 v[116:117], v[106:107], v[116:117]
	v_sub_f32_e32 v119, v158, v159
	v_add_f32_e32 v123, v125, v124
	v_sub_f32_e32 v124, v168, v169
	v_add_f32_e32 v125, v127, v126
	v_sub_f32_e32 v126, v170, v171
	v_add_f32_e32 v127, v157, v156
	v_sub_f32_e32 v136, v172, v173
	v_add_f32_e32 v156, v117, v116
	v_cvt_pk_bf16_f32 v116, v119, v124
	v_cvt_pk_bf16_f32 v117, v126, v136
	v_cvt_pk_bf16_f32 v124, v123, v125
	v_cvt_pk_bf16_f32 v125, v127, v156
	global_store_dwordx2 v[154:155], v[116:117], off
	global_store_dwordx2 v[154:155], v[124:125], off offset:128

.LBB0_202:
	s_andn2_b64 vcc, exec, s[26:27]
	s_cbranch_vccnz .LBB0_204
	s_cmpk_gt_u32 s17, 0x5ff
	s_cselect_b64 vcc, -1, 0
	s_and_b64 s[26:27], vcc, exec
	s_cselect_b32 s26, 0x2040000, s49
	s_cselect_b32 s2, s48, 0xfffffc00
	s_add_u32 s26, s14, s26
	v_add_u32_e32 v109, s2, v122
	s_addc_u32 s27, s15, 0
	v_and_b32_e32 v136, 0xffffff80, v109
	v_lshl_add_u64 v[110:111], s[26:27], 0, v[112:113]
	v_cndmask_b32_e32 v108, 1.0, v167, vcc
	v_lshl_add_u64 v[110:111], v[136:137], 1, v[110:111]
	v_lshlrev_b32_e32 v136, 1, v138
	v_lshl_add_u64 v[110:111], v[110:111], 0, v[136:137]
	v_mul_f32_e32 v104, v118, v186
	v_mul_f32_e32 v105, v118, v187
	v_mul_f32_e32 v106, v118, v188
	v_mul_f32_e32 v107, v118, v189
	v_mul_f32_e32 v109, 0.15915494, v104
	v_mul_f32_e32 v112, 0.15915494, v105
	v_mul_f32_e32 v113, 0.15915494, v106
	v_mul_f32_e32 v114, 0.15915494, v107
	v_rndne_f32_e32 v109, v109
	v_rndne_f32_e32 v112, v112
	v_rndne_f32_e32 v113, v113
	v_rndne_f32_e32 v114, v114
	v_fmac_f32_e32 v104, 0xc0c90fdb, v109
	v_fmac_f32_e32 v105, 0xc0c90fdb, v112
	v_fmac_f32_e32 v106, 0xc0c90fdb, v113
	v_fmac_f32_e32 v107, 0xc0c90fdb, v114
	v_fmac_f32_e32 v104, 0x343bbd2e, v109
	v_fmac_f32_e32 v105, 0x343bbd2e, v112
	v_fmac_f32_e32 v106, 0x343bbd2e, v113
	v_fmac_f32_e32 v107, 0x343bbd2e, v114
	v_mul_f32_e32 v109, 0.15915494, v104
	v_mul_f32_e32 v112, 0.15915494, v105
	v_mul_f32_e32 v113, 0.15915494, v106
	v_mul_f32_e32 v115, 0.15915494, v107
	v_sin_f32_e32 v104, v109
	v_cos_f32_e32 v105, v109
	v_sin_f32_e32 v106, v112
	v_cos_f32_e32 v107, v112
	v_sin_f32_e32 v112, v113
	v_cos_f32_e32 v113, v113
	v_sin_f32_e32 v114, v115
	v_cos_f32_e32 v115, v115
	v_pk_mul_f32 v[104:105], v[108:109], v[104:105] op_sel_hi:[0,1]
	v_pk_mul_f32 v[106:107], v[108:109], v[106:107] op_sel_hi:[0,1]
	v_pk_mul_f32 v[112:113], v[108:109], v[112:113] op_sel_hi:[0,1]
	v_pk_mul_f32 v[108:109], v[108:109], v[114:115] op_sel_hi:[0,1]
	v_pk_mul_f32 v[114:115], v[100:101], v[104:105] op_sel:[0,1] op_sel_hi:[1,0]
	v_pk_mul_f32 v[104:105], v[100:101], v[104:105]
	v_pk_mul_f32 v[116:117], v[102:103], v[106:107] op_sel:[0,1] op_sel_hi:[1,0]
	v_pk_mul_f32 v[118:119], v[96:97], v[112:113] op_sel:[0,1] op_sel_hi:[1,0]
	v_pk_mul_f32 v[106:107], v[102:103], v[106:107]
	v_pk_mul_f32 v[112:113], v[96:97], v[112:113]
	v_pk_mul_f32 v[124:125], v[98:99], v[108:109] op_sel:[0,1] op_sel_hi:[1,0]
	v_sub_f32_e32 v114, v114, v115
	v_add_f32_e32 v115, v105, v104
	v_sub_f32_e32 v104, v116, v117
	v_sub_f32_e32 v105, v118, v119
	v_pk_mul_f32 v[108:109], v[98:99], v[108:109]
	v_add_f32_e32 v106, v107, v106
	v_add_f32_e32 v107, v113, v112
	v_sub_f32_e32 v112, v124, v125
	v_cvt_pk_bf16_f32 v104, v114, v104
	v_cvt_pk_bf16_f32 v105, v105, v112
	v_add_f32_e32 v108, v109, v108
	v_cvt_pk_bf16_f32 v106, v115, v106
	v_cvt_pk_bf16_f32 v107, v107, v108
	global_store_dwordx2 v[110:111], v[104:105], off
	global_store_dwordx2 v[110:111], v[106:107], off offset:128

.LBB0_209:
	s_andn2_b64 vcc, exec, s[26:27]
	s_cbranch_vccnz .LBB0_211
	s_cmpk_gt_u32 s17, 0x5ff
	s_cselect_b64 vcc, -1, 0
	s_and_b64 s[26:27], vcc, exec
	s_cselect_b32 s2, s48, 0xfffffc00
	v_add_u32_e32 v101, s2, v151
	v_and_b32_e32 v136, 0xffffff00, v101
	s_cselect_b32 s26, 0x2040000, s49
	s_add_u32 s26, s14, s26
	v_cndmask_b32_e32 v100, 1.0, v167, vcc
	s_addc_u32 s27, s15, 0
	v_lshl_add_u64 v[108:109], s[26:27], 0, v[96:97]
	v_lshl_add_u64 v[108:109], v[136:137], 1, v[108:109]
	v_lshlrev_b32_e32 v136, 1, v138
	v_lshl_add_u64 v[108:109], v[108:109], 0, v[136:137]
	v_mul_f32_e32 v101, v102, v186
	v_mul_f32_e32 v103, v102, v187
	v_mul_f32_e32 v104, v102, v188
	v_mul_f32_e32 v105, v102, v189
	v_mul_f32_e32 v106, 0.15915494, v101
	v_mul_f32_e32 v107, 0.15915494, v103
	v_mul_f32_e32 v110, 0.15915494, v104
	v_mul_f32_e32 v111, 0.15915494, v105
	v_rndne_f32_e32 v106, v106
	v_rndne_f32_e32 v107, v107
	v_rndne_f32_e32 v110, v110
	v_rndne_f32_e32 v111, v111
	v_fmac_f32_e32 v101, 0xc0c90fdb, v106
	v_fmac_f32_e32 v103, 0xc0c90fdb, v107
	v_fmac_f32_e32 v104, 0xc0c90fdb, v110
	v_fmac_f32_e32 v105, 0xc0c90fdb, v111
	v_fmac_f32_e32 v101, 0x343bbd2e, v106
	v_fmac_f32_e32 v103, 0x343bbd2e, v107
	v_fmac_f32_e32 v104, 0x343bbd2e, v110
	v_fmac_f32_e32 v105, 0x343bbd2e, v111
	v_mul_f32_e32 v101, 0.15915494, v101
	v_mul_f32_e32 v103, 0.15915494, v103
	v_mul_f32_e32 v111, 0.15915494, v104
	v_mul_f32_e32 v113, 0.15915494, v105
	v_sin_f32_e32 v104, v101
	v_cos_f32_e32 v105, v101
	v_sin_f32_e32 v106, v103
	v_cos_f32_e32 v107, v103
	v_sin_f32_e32 v110, v111
	v_cos_f32_e32 v111, v111
	v_sin_f32_e32 v112, v113
	v_cos_f32_e32 v113, v113
	v_pk_mul_f32 v[104:105], v[100:101], v[104:105] op_sel_hi:[0,1]
	v_pk_mul_f32 v[106:107], v[100:101], v[106:107] op_sel_hi:[0,1]
	v_pk_mul_f32 v[110:111], v[100:101], v[110:111] op_sel_hi:[0,1]
	v_pk_mul_f32 v[100:101], v[100:101], v[112:113] op_sel_hi:[0,1]
	v_pk_mul_f32 v[112:113], v[92:93], v[104:105] op_sel:[0,1] op_sel_hi:[1,0]
	v_pk_mul_f32 v[104:105], v[92:93], v[104:105]
	v_pk_mul_f32 v[114:115], v[94:95], v[106:107] op_sel:[0,1] op_sel_hi:[1,0]
	v_pk_mul_f32 v[106:107], v[94:95], v[106:107]
	v_pk_mul_f32 v[116:117], v[88:89], v[110:111] op_sel:[0,1] op_sel_hi:[1,0]
	v_pk_mul_f32 v[110:111], v[88:89], v[110:111]
	v_pk_mul_f32 v[118:119], v[90:91], v[100:101] op_sel:[0,1] op_sel_hi:[1,0]
	v_pk_mul_f32 v[100:101], v[90:91], v[100:101]
	v_sub_f32_e32 v103, v112, v113
	v_add_f32_e32 v104, v105, v104
	v_sub_f32_e32 v105, v114, v115
	v_add_f32_e32 v106, v107, v106
	v_sub_f32_e32 v107, v116, v117
	v_add_f32_e32 v110, v111, v110
	v_sub_f32_e32 v111, v118, v119
	v_add_f32_e32 v112, v101, v100
	v_cvt_pk_bf16_f32 v100, v103, v105
	v_cvt_pk_bf16_f32 v101, v107, v111
	v_cvt_pk_bf16_f32 v104, v104, v106
	v_cvt_pk_bf16_f32 v105, v110, v112
	global_store_dwordx2 v[108:109], v[100:101], off
	global_store_dwordx2 v[108:109], v[104:105], off offset:128

.LBB0_216:
	s_andn2_b64 vcc, exec, s[26:27]
	s_cbranch_vccnz .LBB0_218
	s_cmpk_gt_u32 s17, 0x5ff
	s_cselect_b64 vcc, -1, 0
	s_and_b64 s[26:27], vcc, exec
	s_cselect_b32 s26, 0x2040000, s49
	s_cselect_b32 s2, s48, 0xfffffc00
	s_add_u32 s26, s14, s26
	v_add_u32_e32 v93, s2, v122
	s_addc_u32 s27, s15, 0
	v_and_b32_e32 v136, 0xffffff80, v93
	v_lshl_add_u64 v[94:95], s[26:27], 0, v[96:97]
	v_cndmask_b32_e32 v92, 1.0, v167, vcc
	v_lshl_add_u64 v[94:95], v[136:137], 1, v[94:95]
	v_lshlrev_b32_e32 v136, 1, v138
	v_lshl_add_u64 v[94:95], v[94:95], 0, v[136:137]
	v_mul_f32_e32 v88, v102, v186
	v_mul_f32_e32 v89, v102, v187
	v_mul_f32_e32 v90, v102, v188
	v_mul_f32_e32 v91, v102, v189
	v_mul_f32_e32 v93, 0.15915494, v88
	v_mul_f32_e32 v96, 0.15915494, v89
	v_mul_f32_e32 v97, 0.15915494, v90
	v_mul_f32_e32 v98, 0.15915494, v91
	v_rndne_f32_e32 v93, v93
	v_rndne_f32_e32 v96, v96
	v_rndne_f32_e32 v97, v97
	v_rndne_f32_e32 v98, v98
	v_fmac_f32_e32 v88, 0xc0c90fdb, v93
	v_fmac_f32_e32 v89, 0xc0c90fdb, v96
	v_fmac_f32_e32 v90, 0xc0c90fdb, v97
	v_fmac_f32_e32 v91, 0xc0c90fdb, v98
	v_fmac_f32_e32 v88, 0x343bbd2e, v93
	v_fmac_f32_e32 v89, 0x343bbd2e, v96
	v_fmac_f32_e32 v90, 0x343bbd2e, v97
	v_fmac_f32_e32 v91, 0x343bbd2e, v98
	v_mul_f32_e32 v93, 0.15915494, v88
	v_mul_f32_e32 v96, 0.15915494, v89
	v_mul_f32_e32 v97, 0.15915494, v90
	v_mul_f32_e32 v99, 0.15915494, v91
	v_sin_f32_e32 v88, v93
	v_cos_f32_e32 v89, v93
	v_sin_f32_e32 v90, v96
	v_cos_f32_e32 v91, v96
	v_sin_f32_e32 v96, v97
	v_cos_f32_e32 v97, v97
	v_sin_f32_e32 v98, v99
	v_cos_f32_e32 v99, v99
	v_pk_mul_f32 v[88:89], v[92:93], v[88:89] op_sel_hi:[0,1]
	v_pk_mul_f32 v[90:91], v[92:93], v[90:91] op_sel_hi:[0,1]
	v_pk_mul_f32 v[96:97], v[92:93], v[96:97] op_sel_hi:[0,1]
	v_pk_mul_f32 v[92:93], v[92:93], v[98:99] op_sel_hi:[0,1]
	v_pk_mul_f32 v[98:99], v[84:85], v[88:89] op_sel:[0,1] op_sel_hi:[1,0]
	v_pk_mul_f32 v[88:89], v[84:85], v[88:89]
	v_pk_mul_f32 v[100:101], v[86:87], v[90:91] op_sel:[0,1] op_sel_hi:[1,0]
	v_pk_mul_f32 v[102:103], v[80:81], v[96:97] op_sel:[0,1] op_sel_hi:[1,0]
	v_pk_mul_f32 v[90:91], v[86:87], v[90:91]
	v_pk_mul_f32 v[96:97], v[80:81], v[96:97]
	v_pk_mul_f32 v[104:105], v[82:83], v[92:93] op_sel:[0,1] op_sel_hi:[1,0]
	v_sub_f32_e32 v98, v98, v99
	v_add_f32_e32 v99, v89, v88
	v_sub_f32_e32 v88, v100, v101
	v_sub_f32_e32 v89, v102, v103
	v_pk_mul_f32 v[92:93], v[82:83], v[92:93]
	v_add_f32_e32 v90, v91, v90
	v_add_f32_e32 v91, v97, v96
	v_sub_f32_e32 v96, v104, v105
	v_cvt_pk_bf16_f32 v88, v98, v88
	v_cvt_pk_bf16_f32 v89, v89, v96
	v_add_f32_e32 v92, v93, v92
	v_cvt_pk_bf16_f32 v90, v99, v90
	v_cvt_pk_bf16_f32 v91, v91, v92
	global_store_dwordx2 v[94:95], v[88:89], off
	global_store_dwordx2 v[94:95], v[90:91], off offset:128

.LBB0_223:
	s_andn2_b64 vcc, exec, s[26:27]
	s_cbranch_vccnz .LBB0_225
	s_cmpk_gt_u32 s17, 0x5ff
	s_cselect_b64 vcc, -1, 0
	s_and_b64 s[26:27], vcc, exec
	s_cselect_b32 s2, s48, 0xfffffc00
	v_add_u32_e32 v85, s2, v151
	v_and_b32_e32 v136, 0xffffff00, v85
	s_cselect_b32 s26, 0x2040000, s49
	s_add_u32 s26, s14, s26
	v_cndmask_b32_e32 v84, 1.0, v167, vcc
	s_addc_u32 s27, s15, 0
	v_lshl_add_u64 v[92:93], s[26:27], 0, v[80:81]
	v_lshl_add_u64 v[92:93], v[136:137], 1, v[92:93]
	v_lshlrev_b32_e32 v136, 1, v138
	v_lshl_add_u64 v[92:93], v[92:93], 0, v[136:137]
	v_mul_f32_e32 v85, v86, v186
	v_mul_f32_e32 v87, v86, v187
	v_mul_f32_e32 v88, v86, v188
	v_mul_f32_e32 v89, v86, v189
	v_mul_f32_e32 v90, 0.15915494, v85
	v_mul_f32_e32 v91, 0.15915494, v87
	v_mul_f32_e32 v94, 0.15915494, v88
	v_mul_f32_e32 v95, 0.15915494, v89
	v_rndne_f32_e32 v90, v90
	v_rndne_f32_e32 v91, v91
	v_rndne_f32_e32 v94, v94
	v_rndne_f32_e32 v95, v95
	v_fmac_f32_e32 v85, 0xc0c90fdb, v90
	v_fmac_f32_e32 v87, 0xc0c90fdb, v91
	v_fmac_f32_e32 v88, 0xc0c90fdb, v94
	v_fmac_f32_e32 v89, 0xc0c90fdb, v95
	v_fmac_f32_e32 v85, 0x343bbd2e, v90
	v_fmac_f32_e32 v87, 0x343bbd2e, v91
	v_fmac_f32_e32 v88, 0x343bbd2e, v94
	v_fmac_f32_e32 v89, 0x343bbd2e, v95
	v_mul_f32_e32 v85, 0.15915494, v85
	v_mul_f32_e32 v87, 0.15915494, v87
	v_mul_f32_e32 v95, 0.15915494, v88
	v_mul_f32_e32 v97, 0.15915494, v89
	v_sin_f32_e32 v88, v85
	v_cos_f32_e32 v89, v85
	v_sin_f32_e32 v90, v87
	v_cos_f32_e32 v91, v87
	v_sin_f32_e32 v94, v95
	v_cos_f32_e32 v95, v95
	v_sin_f32_e32 v96, v97
	v_cos_f32_e32 v97, v97
	v_pk_mul_f32 v[88:89], v[84:85], v[88:89] op_sel_hi:[0,1]
	v_pk_mul_f32 v[90:91], v[84:85], v[90:91] op_sel_hi:[0,1]
	v_pk_mul_f32 v[94:95], v[84:85], v[94:95] op_sel_hi:[0,1]
	v_pk_mul_f32 v[84:85], v[84:85], v[96:97] op_sel_hi:[0,1]
	v_pk_mul_f32 v[96:97], v[76:77], v[88:89] op_sel:[0,1] op_sel_hi:[1,0]
	v_pk_mul_f32 v[88:89], v[76:77], v[88:89]
	v_pk_mul_f32 v[98:99], v[78:79], v[90:91] op_sel:[0,1] op_sel_hi:[1,0]
	v_pk_mul_f32 v[90:91], v[78:79], v[90:91]
	v_pk_mul_f32 v[100:101], v[72:73], v[94:95] op_sel:[0,1] op_sel_hi:[1,0]
	v_pk_mul_f32 v[94:95], v[72:73], v[94:95]
	v_pk_mul_f32 v[102:103], v[74:75], v[84:85] op_sel:[0,1] op_sel_hi:[1,0]
	v_pk_mul_f32 v[84:85], v[74:75], v[84:85]
	v_sub_f32_e32 v87, v96, v97
	v_add_f32_e32 v88, v89, v88
	v_sub_f32_e32 v89, v98, v99
	v_add_f32_e32 v90, v91, v90
	v_sub_f32_e32 v91, v100, v101
	v_add_f32_e32 v94, v95, v94
	v_sub_f32_e32 v95, v102, v103
	v_add_f32_e32 v96, v85, v84
	v_cvt_pk_bf16_f32 v84, v87, v89
	v_cvt_pk_bf16_f32 v85, v91, v95
	v_cvt_pk_bf16_f32 v88, v88, v90
	v_cvt_pk_bf16_f32 v89, v94, v96
	global_store_dwordx2 v[92:93], v[84:85], off
	global_store_dwordx2 v[92:93], v[88:89], off offset:128

.LBB0_230:
	s_andn2_b64 vcc, exec, s[26:27]
	s_cbranch_vccnz .LBB0_232
	s_cmpk_gt_u32 s17, 0x5ff
	s_cselect_b64 vcc, -1, 0
	s_and_b64 s[26:27], vcc, exec
	s_cselect_b32 s26, 0x2040000, s49
	s_cselect_b32 s2, s48, 0xfffffc00
	s_add_u32 s26, s14, s26
	v_add_u32_e32 v77, s2, v122
	s_addc_u32 s27, s15, 0
	v_and_b32_e32 v136, 0xffffff80, v77
	v_lshl_add_u64 v[78:79], s[26:27], 0, v[80:81]
	v_cndmask_b32_e32 v76, 1.0, v167, vcc
	v_lshl_add_u64 v[78:79], v[136:137], 1, v[78:79]
	v_lshlrev_b32_e32 v136, 1, v138
	v_lshl_add_u64 v[78:79], v[78:79], 0, v[136:137]
	v_mul_f32_e32 v72, v86, v186
	v_mul_f32_e32 v73, v86, v187
	v_mul_f32_e32 v74, v86, v188
	v_mul_f32_e32 v75, v86, v189
	v_mul_f32_e32 v77, 0.15915494, v72
	v_mul_f32_e32 v80, 0.15915494, v73
	v_mul_f32_e32 v81, 0.15915494, v74
	v_mul_f32_e32 v82, 0.15915494, v75
	v_rndne_f32_e32 v77, v77
	v_rndne_f32_e32 v80, v80
	v_rndne_f32_e32 v81, v81
	v_rndne_f32_e32 v82, v82
	v_fmac_f32_e32 v72, 0xc0c90fdb, v77
	v_fmac_f32_e32 v73, 0xc0c90fdb, v80
	v_fmac_f32_e32 v74, 0xc0c90fdb, v81
	v_fmac_f32_e32 v75, 0xc0c90fdb, v82
	v_fmac_f32_e32 v72, 0x343bbd2e, v77
	v_fmac_f32_e32 v73, 0x343bbd2e, v80
	v_fmac_f32_e32 v74, 0x343bbd2e, v81
	v_fmac_f32_e32 v75, 0x343bbd2e, v82
	v_mul_f32_e32 v77, 0.15915494, v72
	v_mul_f32_e32 v80, 0.15915494, v73
	v_mul_f32_e32 v81, 0.15915494, v74
	v_mul_f32_e32 v83, 0.15915494, v75
	v_sin_f32_e32 v72, v77
	v_cos_f32_e32 v73, v77
	v_sin_f32_e32 v74, v80
	v_cos_f32_e32 v75, v80
	v_sin_f32_e32 v80, v81
	v_cos_f32_e32 v81, v81
	v_sin_f32_e32 v82, v83
	v_cos_f32_e32 v83, v83
	v_pk_mul_f32 v[72:73], v[76:77], v[72:73] op_sel_hi:[0,1]
	v_pk_mul_f32 v[74:75], v[76:77], v[74:75] op_sel_hi:[0,1]
	v_pk_mul_f32 v[80:81], v[76:77], v[80:81] op_sel_hi:[0,1]
	v_pk_mul_f32 v[76:77], v[76:77], v[82:83] op_sel_hi:[0,1]
	v_pk_mul_f32 v[82:83], v[68:69], v[72:73] op_sel:[0,1] op_sel_hi:[1,0]
	v_pk_mul_f32 v[72:73], v[68:69], v[72:73]
	v_pk_mul_f32 v[84:85], v[70:71], v[74:75] op_sel:[0,1] op_sel_hi:[1,0]
	v_pk_mul_f32 v[86:87], v[64:65], v[80:81] op_sel:[0,1] op_sel_hi:[1,0]
	v_pk_mul_f32 v[74:75], v[70:71], v[74:75]
	v_pk_mul_f32 v[80:81], v[64:65], v[80:81]
	v_pk_mul_f32 v[88:89], v[66:67], v[76:77] op_sel:[0,1] op_sel_hi:[1,0]
	v_sub_f32_e32 v82, v82, v83
	v_add_f32_e32 v83, v73, v72
	v_sub_f32_e32 v72, v84, v85
	v_sub_f32_e32 v73, v86, v87
	v_pk_mul_f32 v[76:77], v[66:67], v[76:77]
	v_add_f32_e32 v74, v75, v74
	v_add_f32_e32 v75, v81, v80
	v_sub_f32_e32 v80, v88, v89
	v_cvt_pk_bf16_f32 v72, v82, v72
	v_cvt_pk_bf16_f32 v73, v73, v80
	v_add_f32_e32 v76, v77, v76
	v_cvt_pk_bf16_f32 v74, v83, v74
	v_cvt_pk_bf16_f32 v75, v75, v76
	global_store_dwordx2 v[78:79], v[72:73], off
	global_store_dwordx2 v[78:79], v[74:75], off offset:128

.LBB0_237:
	s_andn2_b64 vcc, exec, s[26:27]
	s_cbranch_vccnz .LBB0_239
	s_cmpk_gt_u32 s17, 0x5ff
	s_cselect_b64 vcc, -1, 0
	s_and_b64 s[26:27], vcc, exec
	s_cselect_b32 s2, s48, 0xfffffc00
	v_add_u32_e32 v69, s2, v151
	v_and_b32_e32 v136, 0xffffff00, v69
	s_cselect_b32 s26, 0x2040000, s49
	s_add_u32 s26, s14, s26
	v_cndmask_b32_e32 v68, 1.0, v167, vcc
	s_addc_u32 s27, s15, 0
	v_lshl_add_u64 v[76:77], s[26:27], 0, v[64:65]
	v_lshl_add_u64 v[76:77], v[136:137], 1, v[76:77]
	v_lshlrev_b32_e32 v136, 1, v138
	v_lshl_add_u64 v[76:77], v[76:77], 0, v[136:137]
	v_mul_f32_e32 v69, v70, v186
	v_mul_f32_e32 v71, v70, v187
	v_mul_f32_e32 v72, v70, v188
	v_mul_f32_e32 v73, v70, v189
	v_mul_f32_e32 v74, 0.15915494, v69
	v_mul_f32_e32 v75, 0.15915494, v71
	v_mul_f32_e32 v78, 0.15915494, v72
	v_mul_f32_e32 v79, 0.15915494, v73
	v_rndne_f32_e32 v74, v74
	v_rndne_f32_e32 v75, v75
	v_rndne_f32_e32 v78, v78
	v_rndne_f32_e32 v79, v79
	v_fmac_f32_e32 v69, 0xc0c90fdb, v74
	v_fmac_f32_e32 v71, 0xc0c90fdb, v75
	v_fmac_f32_e32 v72, 0xc0c90fdb, v78
	v_fmac_f32_e32 v73, 0xc0c90fdb, v79
	v_fmac_f32_e32 v69, 0x343bbd2e, v74
	v_fmac_f32_e32 v71, 0x343bbd2e, v75
	v_fmac_f32_e32 v72, 0x343bbd2e, v78
	v_fmac_f32_e32 v73, 0x343bbd2e, v79
	v_mul_f32_e32 v69, 0.15915494, v69
	v_mul_f32_e32 v71, 0.15915494, v71
	v_mul_f32_e32 v79, 0.15915494, v72
	v_mul_f32_e32 v81, 0.15915494, v73
	v_sin_f32_e32 v72, v69
	v_cos_f32_e32 v73, v69
	v_sin_f32_e32 v74, v71
	v_cos_f32_e32 v75, v71
	v_sin_f32_e32 v78, v79
	v_cos_f32_e32 v79, v79
	v_sin_f32_e32 v80, v81
	v_cos_f32_e32 v81, v81
	v_pk_mul_f32 v[72:73], v[68:69], v[72:73] op_sel_hi:[0,1]
	v_pk_mul_f32 v[74:75], v[68:69], v[74:75] op_sel_hi:[0,1]
	v_pk_mul_f32 v[78:79], v[68:69], v[78:79] op_sel_hi:[0,1]
	v_pk_mul_f32 v[68:69], v[68:69], v[80:81] op_sel_hi:[0,1]
	v_pk_mul_f32 v[80:81], v[60:61], v[72:73] op_sel:[0,1] op_sel_hi:[1,0]
	v_pk_mul_f32 v[72:73], v[60:61], v[72:73]
	v_pk_mul_f32 v[82:83], v[62:63], v[74:75] op_sel:[0,1] op_sel_hi:[1,0]
	v_pk_mul_f32 v[74:75], v[62:63], v[74:75]
	v_pk_mul_f32 v[84:85], v[56:57], v[78:79] op_sel:[0,1] op_sel_hi:[1,0]
	v_pk_mul_f32 v[78:79], v[56:57], v[78:79]
	v_pk_mul_f32 v[86:87], v[58:59], v[68:69] op_sel:[0,1] op_sel_hi:[1,0]
	v_pk_mul_f32 v[68:69], v[58:59], v[68:69]
	v_sub_f32_e32 v71, v80, v81
	v_add_f32_e32 v72, v73, v72
	v_sub_f32_e32 v73, v82, v83
	v_add_f32_e32 v74, v75, v74
	v_sub_f32_e32 v75, v84, v85
	v_add_f32_e32 v78, v79, v78
	v_sub_f32_e32 v79, v86, v87
	v_add_f32_e32 v80, v69, v68
	v_cvt_pk_bf16_f32 v68, v71, v73
	v_cvt_pk_bf16_f32 v69, v75, v79
	v_cvt_pk_bf16_f32 v72, v72, v74
	v_cvt_pk_bf16_f32 v73, v78, v80
	global_store_dwordx2 v[76:77], v[68:69], off
	global_store_dwordx2 v[76:77], v[72:73], off offset:128

.LBB0_244:
	s_andn2_b64 vcc, exec, s[26:27]
	s_cbranch_vccnz .LBB0_246
	s_cmpk_gt_u32 s17, 0x5ff
	s_cselect_b64 vcc, -1, 0
	s_and_b64 s[26:27], vcc, exec
	s_cselect_b32 s26, 0x2040000, s49
	s_cselect_b32 s2, s48, 0xfffffc00
	s_add_u32 s26, s14, s26
	v_add_u32_e32 v61, s2, v122
	s_addc_u32 s27, s15, 0
	v_and_b32_e32 v136, 0xffffff80, v61
	v_lshl_add_u64 v[62:63], s[26:27], 0, v[64:65]
	v_cndmask_b32_e32 v60, 1.0, v167, vcc
	v_lshl_add_u64 v[62:63], v[136:137], 1, v[62:63]
	v_lshlrev_b32_e32 v136, 1, v138
	v_lshl_add_u64 v[62:63], v[62:63], 0, v[136:137]
	v_mul_f32_e32 v56, v70, v186
	v_mul_f32_e32 v57, v70, v187
	v_mul_f32_e32 v58, v70, v188
	v_mul_f32_e32 v59, v70, v189
	v_mul_f32_e32 v61, 0.15915494, v56
	v_mul_f32_e32 v64, 0.15915494, v57
	v_mul_f32_e32 v65, 0.15915494, v58
	v_mul_f32_e32 v66, 0.15915494, v59
	v_rndne_f32_e32 v61, v61
	v_rndne_f32_e32 v64, v64
	v_rndne_f32_e32 v65, v65
	v_rndne_f32_e32 v66, v66
	v_fmac_f32_e32 v56, 0xc0c90fdb, v61
	v_fmac_f32_e32 v57, 0xc0c90fdb, v64
	v_fmac_f32_e32 v58, 0xc0c90fdb, v65
	v_fmac_f32_e32 v59, 0xc0c90fdb, v66
	v_fmac_f32_e32 v56, 0x343bbd2e, v61
	v_fmac_f32_e32 v57, 0x343bbd2e, v64
	v_fmac_f32_e32 v58, 0x343bbd2e, v65
	v_fmac_f32_e32 v59, 0x343bbd2e, v66
	v_mul_f32_e32 v61, 0.15915494, v56
	v_mul_f32_e32 v64, 0.15915494, v57
	v_mul_f32_e32 v65, 0.15915494, v58
	v_mul_f32_e32 v67, 0.15915494, v59
	v_sin_f32_e32 v56, v61
	v_cos_f32_e32 v57, v61
	v_sin_f32_e32 v58, v64
	v_cos_f32_e32 v59, v64
	v_sin_f32_e32 v64, v65
	v_cos_f32_e32 v65, v65
	v_sin_f32_e32 v66, v67
	v_cos_f32_e32 v67, v67
	v_pk_mul_f32 v[56:57], v[60:61], v[56:57] op_sel_hi:[0,1]
	v_pk_mul_f32 v[58:59], v[60:61], v[58:59] op_sel_hi:[0,1]
	v_pk_mul_f32 v[64:65], v[60:61], v[64:65] op_sel_hi:[0,1]
	v_pk_mul_f32 v[60:61], v[60:61], v[66:67] op_sel_hi:[0,1]
	v_pk_mul_f32 v[66:67], v[52:53], v[56:57] op_sel:[0,1] op_sel_hi:[1,0]
	v_pk_mul_f32 v[56:57], v[52:53], v[56:57]
	v_pk_mul_f32 v[68:69], v[54:55], v[58:59] op_sel:[0,1] op_sel_hi:[1,0]
	v_pk_mul_f32 v[70:71], v[48:49], v[64:65] op_sel:[0,1] op_sel_hi:[1,0]
	v_pk_mul_f32 v[58:59], v[54:55], v[58:59]
	v_pk_mul_f32 v[64:65], v[48:49], v[64:65]
	v_pk_mul_f32 v[72:73], v[50:51], v[60:61] op_sel:[0,1] op_sel_hi:[1,0]
	v_sub_f32_e32 v66, v66, v67
	v_add_f32_e32 v67, v57, v56
	v_sub_f32_e32 v56, v68, v69
	v_sub_f32_e32 v57, v70, v71
	v_pk_mul_f32 v[60:61], v[50:51], v[60:61]
	v_add_f32_e32 v58, v59, v58
	v_add_f32_e32 v59, v65, v64
	v_sub_f32_e32 v64, v72, v73
	v_cvt_pk_bf16_f32 v56, v66, v56
	v_cvt_pk_bf16_f32 v57, v57, v64
	v_add_f32_e32 v60, v61, v60
	v_cvt_pk_bf16_f32 v58, v67, v58
	v_cvt_pk_bf16_f32 v59, v59, v60
	global_store_dwordx2 v[62:63], v[56:57], off
	global_store_dwordx2 v[62:63], v[58:59], off offset:128

.LBB0_251:
	s_andn2_b64 vcc, exec, s[26:27]
	s_cbranch_vccnz .LBB0_253
	s_cmpk_gt_u32 s17, 0x5ff
	s_cselect_b64 vcc, -1, 0
	s_and_b64 s[26:27], vcc, exec
	s_cselect_b32 s2, s48, 0xfffffc00
	v_add_u32_e32 v53, s2, v151
	v_and_b32_e32 v136, 0xffffff00, v53
	s_cselect_b32 s26, 0x2040000, s49
	s_add_u32 s26, s14, s26
	v_cndmask_b32_e32 v52, 1.0, v167, vcc
	s_addc_u32 s27, s15, 0
	v_lshl_add_u64 v[60:61], s[26:27], 0, v[48:49]
	v_lshl_add_u64 v[60:61], v[136:137], 1, v[60:61]
	v_lshlrev_b32_e32 v136, 1, v138
	v_lshl_add_u64 v[60:61], v[60:61], 0, v[136:137]
	v_mul_f32_e32 v53, v54, v186
	v_mul_f32_e32 v55, v54, v187
	v_mul_f32_e32 v56, v54, v188
	v_mul_f32_e32 v57, v54, v189
	v_mul_f32_e32 v58, 0.15915494, v53
	v_mul_f32_e32 v59, 0.15915494, v55
	v_mul_f32_e32 v62, 0.15915494, v56
	v_mul_f32_e32 v63, 0.15915494, v57
	v_rndne_f32_e32 v58, v58
	v_rndne_f32_e32 v59, v59
	v_rndne_f32_e32 v62, v62
	v_rndne_f32_e32 v63, v63
	v_fmac_f32_e32 v53, 0xc0c90fdb, v58
	v_fmac_f32_e32 v55, 0xc0c90fdb, v59
	v_fmac_f32_e32 v56, 0xc0c90fdb, v62
	v_fmac_f32_e32 v57, 0xc0c90fdb, v63
	v_fmac_f32_e32 v53, 0x343bbd2e, v58
	v_fmac_f32_e32 v55, 0x343bbd2e, v59
	v_fmac_f32_e32 v56, 0x343bbd2e, v62
	v_fmac_f32_e32 v57, 0x343bbd2e, v63
	v_mul_f32_e32 v53, 0.15915494, v53
	v_mul_f32_e32 v55, 0.15915494, v55
	v_mul_f32_e32 v63, 0.15915494, v56
	v_mul_f32_e32 v65, 0.15915494, v57
	v_sin_f32_e32 v56, v53
	v_cos_f32_e32 v57, v53
	v_sin_f32_e32 v58, v55
	v_cos_f32_e32 v59, v55
	v_sin_f32_e32 v62, v63
	v_cos_f32_e32 v63, v63
	v_sin_f32_e32 v64, v65
	v_cos_f32_e32 v65, v65
	v_pk_mul_f32 v[56:57], v[52:53], v[56:57] op_sel_hi:[0,1]
	v_pk_mul_f32 v[58:59], v[52:53], v[58:59] op_sel_hi:[0,1]
	v_pk_mul_f32 v[62:63], v[52:53], v[62:63] op_sel_hi:[0,1]
	v_pk_mul_f32 v[52:53], v[52:53], v[64:65] op_sel_hi:[0,1]
	v_pk_mul_f32 v[64:65], v[44:45], v[56:57] op_sel:[0,1] op_sel_hi:[1,0]
	v_pk_mul_f32 v[56:57], v[44:45], v[56:57]
	v_pk_mul_f32 v[66:67], v[46:47], v[58:59] op_sel:[0,1] op_sel_hi:[1,0]
	v_pk_mul_f32 v[58:59], v[46:47], v[58:59]
	v_pk_mul_f32 v[68:69], v[40:41], v[62:63] op_sel:[0,1] op_sel_hi:[1,0]
	v_pk_mul_f32 v[62:63], v[40:41], v[62:63]
	v_pk_mul_f32 v[70:71], v[42:43], v[52:53] op_sel:[0,1] op_sel_hi:[1,0]
	v_pk_mul_f32 v[52:53], v[42:43], v[52:53]
	v_sub_f32_e32 v55, v64, v65
	v_add_f32_e32 v56, v57, v56
	v_sub_f32_e32 v57, v66, v67
	v_add_f32_e32 v58, v59, v58
	v_sub_f32_e32 v59, v68, v69
	v_add_f32_e32 v62, v63, v62
	v_sub_f32_e32 v63, v70, v71
	v_add_f32_e32 v64, v53, v52
	v_cvt_pk_bf16_f32 v52, v55, v57
	v_cvt_pk_bf16_f32 v53, v59, v63
	v_cvt_pk_bf16_f32 v56, v56, v58
	v_cvt_pk_bf16_f32 v57, v62, v64
	global_store_dwordx2 v[60:61], v[52:53], off
	global_store_dwordx2 v[60:61], v[56:57], off offset:128

.LBB0_258:
	s_andn2_b64 vcc, exec, s[26:27]
	s_cbranch_vccnz .LBB0_260
	s_cmpk_gt_u32 s17, 0x5ff
	s_cselect_b64 vcc, -1, 0
	s_and_b64 s[26:27], vcc, exec
	s_cselect_b32 s26, 0x2040000, s49
	s_cselect_b32 s2, s48, 0xfffffc00
	s_add_u32 s26, s14, s26
	v_add_u32_e32 v45, s2, v122
	s_addc_u32 s27, s15, 0
	v_and_b32_e32 v136, 0xffffff80, v45
	v_lshl_add_u64 v[46:47], s[26:27], 0, v[48:49]
	v_cndmask_b32_e32 v44, 1.0, v167, vcc
	v_lshl_add_u64 v[46:47], v[136:137], 1, v[46:47]
	v_lshlrev_b32_e32 v136, 1, v138
	v_lshl_add_u64 v[46:47], v[46:47], 0, v[136:137]
	v_mul_f32_e32 v40, v54, v186
	v_mul_f32_e32 v41, v54, v187
	v_mul_f32_e32 v42, v54, v188
	v_mul_f32_e32 v43, v54, v189
	v_mul_f32_e32 v45, 0.15915494, v40
	v_mul_f32_e32 v48, 0.15915494, v41
	v_mul_f32_e32 v49, 0.15915494, v42
	v_mul_f32_e32 v50, 0.15915494, v43
	v_rndne_f32_e32 v45, v45
	v_rndne_f32_e32 v48, v48
	v_rndne_f32_e32 v49, v49
	v_rndne_f32_e32 v50, v50
	v_fmac_f32_e32 v40, 0xc0c90fdb, v45
	v_fmac_f32_e32 v41, 0xc0c90fdb, v48
	v_fmac_f32_e32 v42, 0xc0c90fdb, v49
	v_fmac_f32_e32 v43, 0xc0c90fdb, v50
	v_fmac_f32_e32 v40, 0x343bbd2e, v45
	v_fmac_f32_e32 v41, 0x343bbd2e, v48
	v_fmac_f32_e32 v42, 0x343bbd2e, v49
	v_fmac_f32_e32 v43, 0x343bbd2e, v50
	v_mul_f32_e32 v45, 0.15915494, v40
	v_mul_f32_e32 v48, 0.15915494, v41
	v_mul_f32_e32 v49, 0.15915494, v42
	v_mul_f32_e32 v51, 0.15915494, v43
	v_sin_f32_e32 v40, v45
	v_cos_f32_e32 v41, v45
	v_sin_f32_e32 v42, v48
	v_cos_f32_e32 v43, v48
	v_sin_f32_e32 v48, v49
	v_cos_f32_e32 v49, v49
	v_sin_f32_e32 v50, v51
	v_cos_f32_e32 v51, v51
	v_pk_mul_f32 v[40:41], v[44:45], v[40:41] op_sel_hi:[0,1]
	v_pk_mul_f32 v[42:43], v[44:45], v[42:43] op_sel_hi:[0,1]
	v_pk_mul_f32 v[48:49], v[44:45], v[48:49] op_sel_hi:[0,1]
	v_pk_mul_f32 v[44:45], v[44:45], v[50:51] op_sel_hi:[0,1]
	v_pk_mul_f32 v[50:51], v[36:37], v[40:41] op_sel:[0,1] op_sel_hi:[1,0]
	v_pk_mul_f32 v[40:41], v[36:37], v[40:41]
	v_pk_mul_f32 v[52:53], v[38:39], v[42:43] op_sel:[0,1] op_sel_hi:[1,0]
	v_pk_mul_f32 v[54:55], v[32:33], v[48:49] op_sel:[0,1] op_sel_hi:[1,0]
	v_pk_mul_f32 v[42:43], v[38:39], v[42:43]
	v_pk_mul_f32 v[48:49], v[32:33], v[48:49]
	v_pk_mul_f32 v[56:57], v[34:35], v[44:45] op_sel:[0,1] op_sel_hi:[1,0]
	v_sub_f32_e32 v50, v50, v51
	v_add_f32_e32 v51, v41, v40
	v_sub_f32_e32 v40, v52, v53
	v_sub_f32_e32 v41, v54, v55
	v_pk_mul_f32 v[44:45], v[34:35], v[44:45]
	v_add_f32_e32 v42, v43, v42
	v_add_f32_e32 v43, v49, v48
	v_sub_f32_e32 v48, v56, v57
	v_cvt_pk_bf16_f32 v40, v50, v40
	v_cvt_pk_bf16_f32 v41, v41, v48
	v_add_f32_e32 v44, v45, v44
	v_cvt_pk_bf16_f32 v42, v51, v42
	v_cvt_pk_bf16_f32 v43, v43, v44
	global_store_dwordx2 v[46:47], v[40:41], off
	global_store_dwordx2 v[46:47], v[42:43], off offset:128

.LBB0_265:
	s_andn2_b64 vcc, exec, s[26:27]
	s_cbranch_vccnz .LBB0_267
	s_cmpk_gt_u32 s17, 0x5ff
	s_cselect_b64 vcc, -1, 0
	s_and_b64 s[26:27], vcc, exec
	s_cselect_b32 s2, s48, 0xfffffc00
	v_add_u32_e32 v37, s2, v151
	v_and_b32_e32 v136, 0xffffff00, v37
	s_cselect_b32 s26, 0x2040000, s49
	s_add_u32 s26, s14, s26
	v_cndmask_b32_e32 v36, 1.0, v167, vcc
	s_addc_u32 s27, s15, 0
	v_lshl_add_u64 v[44:45], s[26:27], 0, v[32:33]
	v_lshl_add_u64 v[44:45], v[136:137], 1, v[44:45]
	v_lshlrev_b32_e32 v136, 1, v138
	v_lshl_add_u64 v[44:45], v[44:45], 0, v[136:137]
	v_mul_f32_e32 v37, v38, v186
	v_mul_f32_e32 v39, v38, v187
	v_mul_f32_e32 v40, v38, v188
	v_mul_f32_e32 v41, v38, v189
	v_mul_f32_e32 v42, 0.15915494, v37
	v_mul_f32_e32 v43, 0.15915494, v39
	v_mul_f32_e32 v46, 0.15915494, v40
	v_mul_f32_e32 v47, 0.15915494, v41
	v_rndne_f32_e32 v42, v42
	v_rndne_f32_e32 v43, v43
	v_rndne_f32_e32 v46, v46
	v_rndne_f32_e32 v47, v47
	v_fmac_f32_e32 v37, 0xc0c90fdb, v42
	v_fmac_f32_e32 v39, 0xc0c90fdb, v43
	v_fmac_f32_e32 v40, 0xc0c90fdb, v46
	v_fmac_f32_e32 v41, 0xc0c90fdb, v47
	v_fmac_f32_e32 v37, 0x343bbd2e, v42
	v_fmac_f32_e32 v39, 0x343bbd2e, v43
	v_fmac_f32_e32 v40, 0x343bbd2e, v46
	v_fmac_f32_e32 v41, 0x343bbd2e, v47
	v_mul_f32_e32 v37, 0.15915494, v37
	v_mul_f32_e32 v39, 0.15915494, v39
	v_mul_f32_e32 v47, 0.15915494, v40
	v_mul_f32_e32 v49, 0.15915494, v41
	v_sin_f32_e32 v40, v37
	v_cos_f32_e32 v41, v37
	v_sin_f32_e32 v42, v39
	v_cos_f32_e32 v43, v39
	v_sin_f32_e32 v46, v47
	v_cos_f32_e32 v47, v47
	v_sin_f32_e32 v48, v49
	v_cos_f32_e32 v49, v49
	v_pk_mul_f32 v[40:41], v[36:37], v[40:41] op_sel_hi:[0,1]
	v_pk_mul_f32 v[42:43], v[36:37], v[42:43] op_sel_hi:[0,1]
	v_pk_mul_f32 v[46:47], v[36:37], v[46:47] op_sel_hi:[0,1]
	v_pk_mul_f32 v[36:37], v[36:37], v[48:49] op_sel_hi:[0,1]
	v_pk_mul_f32 v[48:49], v[28:29], v[40:41] op_sel:[0,1] op_sel_hi:[1,0]
	v_pk_mul_f32 v[40:41], v[28:29], v[40:41]
	v_pk_mul_f32 v[50:51], v[30:31], v[42:43] op_sel:[0,1] op_sel_hi:[1,0]
	v_pk_mul_f32 v[42:43], v[30:31], v[42:43]
	v_pk_mul_f32 v[52:53], v[24:25], v[46:47] op_sel:[0,1] op_sel_hi:[1,0]
	v_pk_mul_f32 v[46:47], v[24:25], v[46:47]
	v_pk_mul_f32 v[54:55], v[26:27], v[36:37] op_sel:[0,1] op_sel_hi:[1,0]
	v_pk_mul_f32 v[36:37], v[26:27], v[36:37]
	v_sub_f32_e32 v39, v48, v49
	v_add_f32_e32 v40, v41, v40
	v_sub_f32_e32 v41, v50, v51
	v_add_f32_e32 v42, v43, v42
	v_sub_f32_e32 v43, v52, v53
	v_add_f32_e32 v46, v47, v46
	v_sub_f32_e32 v47, v54, v55
	v_add_f32_e32 v48, v37, v36
	v_cvt_pk_bf16_f32 v36, v39, v41
	v_cvt_pk_bf16_f32 v37, v43, v47
	v_cvt_pk_bf16_f32 v40, v40, v42
	v_cvt_pk_bf16_f32 v41, v46, v48
	global_store_dwordx2 v[44:45], v[36:37], off
	global_store_dwordx2 v[44:45], v[40:41], off offset:128

.LBB0_272:
	s_andn2_b64 vcc, exec, s[26:27]
	s_cbranch_vccnz .LBB0_274
	s_cmpk_gt_u32 s17, 0x5ff
	s_cselect_b64 vcc, -1, 0
	s_and_b64 s[26:27], vcc, exec
	s_cselect_b32 s26, 0x2040000, s49
	s_cselect_b32 s2, s48, 0xfffffc00
	s_add_u32 s26, s14, s26
	v_add_u32_e32 v29, s2, v122
	s_addc_u32 s27, s15, 0
	v_and_b32_e32 v136, 0xffffff80, v29
	v_lshl_add_u64 v[30:31], s[26:27], 0, v[32:33]
	v_cndmask_b32_e32 v28, 1.0, v167, vcc
	v_lshl_add_u64 v[30:31], v[136:137], 1, v[30:31]
	v_lshlrev_b32_e32 v136, 1, v138
	v_lshl_add_u64 v[30:31], v[30:31], 0, v[136:137]
	v_mul_f32_e32 v24, v38, v186
	v_mul_f32_e32 v25, v38, v187
	v_mul_f32_e32 v26, v38, v188
	v_mul_f32_e32 v27, v38, v189
	v_mul_f32_e32 v29, 0.15915494, v24
	v_mul_f32_e32 v32, 0.15915494, v25
	v_mul_f32_e32 v33, 0.15915494, v26
	v_mul_f32_e32 v34, 0.15915494, v27
	v_rndne_f32_e32 v29, v29
	v_rndne_f32_e32 v32, v32
	v_rndne_f32_e32 v33, v33
	v_rndne_f32_e32 v34, v34
	v_fmac_f32_e32 v24, 0xc0c90fdb, v29
	v_fmac_f32_e32 v25, 0xc0c90fdb, v32
	v_fmac_f32_e32 v26, 0xc0c90fdb, v33
	v_fmac_f32_e32 v27, 0xc0c90fdb, v34
	v_fmac_f32_e32 v24, 0x343bbd2e, v29
	v_fmac_f32_e32 v25, 0x343bbd2e, v32
	v_fmac_f32_e32 v26, 0x343bbd2e, v33
	v_fmac_f32_e32 v27, 0x343bbd2e, v34
	v_mul_f32_e32 v29, 0.15915494, v24
	v_mul_f32_e32 v32, 0.15915494, v25
	v_mul_f32_e32 v33, 0.15915494, v26
	v_mul_f32_e32 v35, 0.15915494, v27
	v_sin_f32_e32 v24, v29
	v_cos_f32_e32 v25, v29
	v_sin_f32_e32 v26, v32
	v_cos_f32_e32 v27, v32
	v_sin_f32_e32 v32, v33
	v_cos_f32_e32 v33, v33
	v_sin_f32_e32 v34, v35
	v_cos_f32_e32 v35, v35
	v_pk_mul_f32 v[24:25], v[28:29], v[24:25] op_sel_hi:[0,1]
	v_pk_mul_f32 v[26:27], v[28:29], v[26:27] op_sel_hi:[0,1]
	v_pk_mul_f32 v[32:33], v[28:29], v[32:33] op_sel_hi:[0,1]
	v_pk_mul_f32 v[28:29], v[28:29], v[34:35] op_sel_hi:[0,1]
	v_pk_mul_f32 v[34:35], v[20:21], v[24:25] op_sel:[0,1] op_sel_hi:[1,0]
	v_pk_mul_f32 v[24:25], v[20:21], v[24:25]
	v_pk_mul_f32 v[36:37], v[22:23], v[26:27] op_sel:[0,1] op_sel_hi:[1,0]
	v_pk_mul_f32 v[38:39], v[16:17], v[32:33] op_sel:[0,1] op_sel_hi:[1,0]
	v_pk_mul_f32 v[26:27], v[22:23], v[26:27]
	v_pk_mul_f32 v[32:33], v[16:17], v[32:33]
	v_pk_mul_f32 v[40:41], v[18:19], v[28:29] op_sel:[0,1] op_sel_hi:[1,0]
	v_sub_f32_e32 v34, v34, v35
	v_add_f32_e32 v35, v25, v24
	v_sub_f32_e32 v24, v36, v37
	v_sub_f32_e32 v25, v38, v39
	v_pk_mul_f32 v[28:29], v[18:19], v[28:29]
	v_add_f32_e32 v26, v27, v26
	v_add_f32_e32 v27, v33, v32
	v_sub_f32_e32 v32, v40, v41
	v_cvt_pk_bf16_f32 v24, v34, v24
	v_cvt_pk_bf16_f32 v25, v25, v32
	v_add_f32_e32 v28, v29, v28
	v_cvt_pk_bf16_f32 v26, v35, v26
	v_cvt_pk_bf16_f32 v27, v27, v28
	global_store_dwordx2 v[30:31], v[24:25], off
	global_store_dwordx2 v[30:31], v[26:27], off offset:128

.LBB0_279:
	s_andn2_b64 vcc, exec, s[24:25]
	s_cbranch_vccnz .LBB0_281
	s_cmpk_gt_u32 s17, 0x5ff
	s_cselect_b64 vcc, -1, 0
	s_and_b64 s[24:25], vcc, exec
	s_cselect_b32 s2, s48, 0xfffffc00
	v_add_u32_e32 v21, s2, v151
	v_and_b32_e32 v136, 0xffffff00, v21
	s_cselect_b32 s24, 0x2040000, s49
	s_add_u32 s24, s14, s24
	v_cndmask_b32_e32 v20, 1.0, v167, vcc
	s_addc_u32 s25, s15, 0
	v_lshl_add_u64 v[28:29], s[24:25], 0, v[16:17]
	v_lshl_add_u64 v[28:29], v[136:137], 1, v[28:29]
	v_lshlrev_b32_e32 v136, 1, v138
	v_lshl_add_u64 v[28:29], v[28:29], 0, v[136:137]
	v_mul_f32_e32 v21, v22, v186
	v_mul_f32_e32 v23, v22, v187
	v_mul_f32_e32 v24, v22, v188
	v_mul_f32_e32 v25, v22, v189
	v_mul_f32_e32 v26, 0.15915494, v21
	v_mul_f32_e32 v27, 0.15915494, v23
	v_mul_f32_e32 v30, 0.15915494, v24
	v_mul_f32_e32 v31, 0.15915494, v25
	v_rndne_f32_e32 v26, v26
	v_rndne_f32_e32 v27, v27
	v_rndne_f32_e32 v30, v30
	v_rndne_f32_e32 v31, v31
	v_fmac_f32_e32 v21, 0xc0c90fdb, v26
	v_fmac_f32_e32 v23, 0xc0c90fdb, v27
	v_fmac_f32_e32 v24, 0xc0c90fdb, v30
	v_fmac_f32_e32 v25, 0xc0c90fdb, v31
	v_fmac_f32_e32 v21, 0x343bbd2e, v26
	v_fmac_f32_e32 v23, 0x343bbd2e, v27
	v_fmac_f32_e32 v24, 0x343bbd2e, v30
	v_fmac_f32_e32 v25, 0x343bbd2e, v31
	v_mul_f32_e32 v21, 0.15915494, v21
	v_mul_f32_e32 v23, 0.15915494, v23
	v_mul_f32_e32 v31, 0.15915494, v24
	v_mul_f32_e32 v33, 0.15915494, v25
	v_sin_f32_e32 v24, v21
	v_cos_f32_e32 v25, v21
	v_sin_f32_e32 v26, v23
	v_cos_f32_e32 v27, v23
	v_sin_f32_e32 v30, v31
	v_cos_f32_e32 v31, v31
	v_sin_f32_e32 v32, v33
	v_cos_f32_e32 v33, v33
	v_pk_mul_f32 v[24:25], v[20:21], v[24:25] op_sel_hi:[0,1]
	v_pk_mul_f32 v[26:27], v[20:21], v[26:27] op_sel_hi:[0,1]
	v_pk_mul_f32 v[30:31], v[20:21], v[30:31] op_sel_hi:[0,1]
	v_pk_mul_f32 v[20:21], v[20:21], v[32:33] op_sel_hi:[0,1]
	v_pk_mul_f32 v[32:33], v[12:13], v[24:25] op_sel:[0,1] op_sel_hi:[1,0]
	v_pk_mul_f32 v[24:25], v[12:13], v[24:25]
	v_pk_mul_f32 v[34:35], v[14:15], v[26:27] op_sel:[0,1] op_sel_hi:[1,0]
	v_pk_mul_f32 v[26:27], v[14:15], v[26:27]
	v_pk_mul_f32 v[36:37], v[8:9], v[30:31] op_sel:[0,1] op_sel_hi:[1,0]
	v_pk_mul_f32 v[30:31], v[8:9], v[30:31]
	v_pk_mul_f32 v[38:39], v[10:11], v[20:21] op_sel:[0,1] op_sel_hi:[1,0]
	v_pk_mul_f32 v[20:21], v[10:11], v[20:21]
	v_sub_f32_e32 v23, v32, v33
	v_add_f32_e32 v24, v25, v24
	v_sub_f32_e32 v25, v34, v35
	v_add_f32_e32 v26, v27, v26
	v_sub_f32_e32 v27, v36, v37
	v_add_f32_e32 v30, v31, v30
	v_sub_f32_e32 v31, v38, v39
	v_add_f32_e32 v32, v21, v20
	v_cvt_pk_bf16_f32 v20, v23, v25
	v_cvt_pk_bf16_f32 v21, v27, v31
	v_cvt_pk_bf16_f32 v24, v24, v26
	v_cvt_pk_bf16_f32 v25, v30, v32
	global_store_dwordx2 v[28:29], v[20:21], off
	global_store_dwordx2 v[28:29], v[24:25], off offset:128

.LBB0_286:
	s_andn2_b64 vcc, exec, s[8:9]
	s_cbranch_vccnz .LBB0_288
	s_cmpk_gt_u32 s17, 0x5ff
	s_cselect_b64 vcc, -1, 0
	s_and_b64 s[8:9], vcc, exec
	s_cselect_b32 s8, 0x2040000, s49
	s_cselect_b32 s2, s48, 0xfffffc00
	s_add_u32 s8, s14, s8
	v_add_u32_e32 v13, s2, v122
	s_addc_u32 s9, s15, 0
	v_and_b32_e32 v136, 0xffffff80, v13
	v_lshl_add_u64 v[14:15], s[8:9], 0, v[16:17]
	v_cndmask_b32_e32 v12, 1.0, v167, vcc
	v_lshl_add_u64 v[14:15], v[136:137], 1, v[14:15]
	v_lshlrev_b32_e32 v136, 1, v138
	v_lshl_add_u64 v[14:15], v[14:15], 0, v[136:137]
	v_mul_f32_e32 v8, v22, v186
	v_mul_f32_e32 v9, v22, v187
	v_mul_f32_e32 v10, v22, v188
	v_mul_f32_e32 v11, v22, v189
	v_mul_f32_e32 v13, 0.15915494, v8
	v_mul_f32_e32 v16, 0.15915494, v9
	v_mul_f32_e32 v17, 0.15915494, v10
	v_mul_f32_e32 v18, 0.15915494, v11
	v_rndne_f32_e32 v13, v13
	v_rndne_f32_e32 v16, v16
	v_rndne_f32_e32 v17, v17
	v_rndne_f32_e32 v18, v18
	v_fmac_f32_e32 v8, 0xc0c90fdb, v13
	v_fmac_f32_e32 v9, 0xc0c90fdb, v16
	v_fmac_f32_e32 v10, 0xc0c90fdb, v17
	v_fmac_f32_e32 v11, 0xc0c90fdb, v18
	v_fmac_f32_e32 v8, 0x343bbd2e, v13
	v_fmac_f32_e32 v9, 0x343bbd2e, v16
	v_fmac_f32_e32 v10, 0x343bbd2e, v17
	v_fmac_f32_e32 v11, 0x343bbd2e, v18
	v_mul_f32_e32 v13, 0.15915494, v8
	v_mul_f32_e32 v16, 0.15915494, v9
	v_mul_f32_e32 v17, 0.15915494, v10
	v_mul_f32_e32 v19, 0.15915494, v11
	v_sin_f32_e32 v8, v13
	v_cos_f32_e32 v9, v13
	v_sin_f32_e32 v10, v16
	v_cos_f32_e32 v11, v16
	v_sin_f32_e32 v16, v17
	v_cos_f32_e32 v17, v17
	v_sin_f32_e32 v18, v19
	v_cos_f32_e32 v19, v19
	v_pk_mul_f32 v[8:9], v[12:13], v[8:9] op_sel_hi:[0,1]
	v_pk_mul_f32 v[10:11], v[12:13], v[10:11] op_sel_hi:[0,1]
	v_pk_mul_f32 v[16:17], v[12:13], v[16:17] op_sel_hi:[0,1]
	v_pk_mul_f32 v[12:13], v[12:13], v[18:19] op_sel_hi:[0,1]
	v_pk_mul_f32 v[18:19], v[4:5], v[8:9] op_sel:[0,1] op_sel_hi:[1,0]
	v_pk_mul_f32 v[8:9], v[4:5], v[8:9]
	v_pk_mul_f32 v[20:21], v[6:7], v[10:11] op_sel:[0,1] op_sel_hi:[1,0]
	v_pk_mul_f32 v[22:23], v[0:1], v[16:17] op_sel:[0,1] op_sel_hi:[1,0]
	v_pk_mul_f32 v[10:11], v[6:7], v[10:11]
	v_pk_mul_f32 v[16:17], v[0:1], v[16:17]
	v_pk_mul_f32 v[24:25], v[2:3], v[12:13] op_sel:[0,1] op_sel_hi:[1,0]
	v_sub_f32_e32 v18, v18, v19
	v_add_f32_e32 v19, v9, v8
	v_sub_f32_e32 v8, v20, v21
	v_sub_f32_e32 v9, v22, v23
	v_pk_mul_f32 v[12:13], v[2:3], v[12:13]
	v_add_f32_e32 v10, v11, v10
	v_add_f32_e32 v11, v17, v16
	v_sub_f32_e32 v16, v24, v25
	v_cvt_pk_bf16_f32 v8, v18, v8
	v_cvt_pk_bf16_f32 v9, v9, v16
	v_add_f32_e32 v12, v13, v12
	v_cvt_pk_bf16_f32 v10, v19, v10
	v_cvt_pk_bf16_f32 v11, v11, v12
	global_store_dwordx2 v[14:15], v[8:9], off
	global_store_dwordx2 v[14:15], v[10:11], off offset:128

.LBB0_290:
	s_or_b64 exec, exec, s[6:7]
	s_waitcnt vmcnt(16)
	s_andn2_b64 vcc, exec, s[4:5]
	s_mov_b64 s[4:5], -1
	s_cbranch_vccnz .LBB0_171
	s_andn2_b64 vcc, exec, s[0:1]
	s_cbranch_vccnz .LBB0_170
	s_barrier
	s_branch .LBB0_170
